# non-temporal cache hints on the streaming weight-conversion loads and stores of the idle-slot converters
# baseline (speedup 1.0000x reference)
; #define LAS __attribute__((address_space(3)))
; __device__ __forceinline__ int obid() { int t = blockIdx.x; asm volatile("" : "+s"(t)); return t; }
; __device__ void phase_weights(const Params& p, int l, LAS unsigned char* lds) {
;     ...
;     for (int u0 = obid(); u0 < TOT; u0 += 4 * G) {
;         f32x4 v[4][2];
;         { const int k = tid >> 3, cg8 = (tid & 7) * 8;
; #pragma unroll
;           for (int j = 0; j < 4; ++j) { const int u = u0 + j * G; v[j][0] = (f32x4){0.f, 0.f, 0.f, 0.f}; v[j][1] = v[j][0];
;               if (u < TOT) { const WDesc d = wdesc(p, l, u); const float* sp = d.src + (size_t)(d.k0 + k) * d.ldsrc + d.c0 + cg8;
;                   if (cg8 + 3 < d.nvalid) v[j][0] = __builtin_nontemporal_load((const f32x4*)sp); if (cg8 + 7 < d.nvalid) v[j][1] = __builtin_nontemporal_load((const f32x4*)(sp + 4)); } }
; #pragma unroll
;           for (int j = 0; j < 4; ++j)
; #pragma unroll
;               for (int i = 0; i < 2; ++i) { LAS float* Tj = T + j * 4160 + k * 65 + cg8 + 4 * i; Tj[0] = v[j][i][0]; Tj[1] = v[j][i][1]; Tj[2] = v[j][i][2]; Tj[3] = v[j][i][3]; } }
.Lwp7_f0:
	global_load_lds_dwordx4 v22, s[38:39] nt
	s_add_u32 s38, s38, s0
	s_addc_u32 s39, s39, 0
	s_add_i32 m0, s31, 0x400
	v_add_u32_e32 v23, v20, v2
	global_load_lds_dwordx4 v23, s[38:39] nt
	s_add_u32 s38, s38, s0
	s_addc_u32 s39, s39, 0
	s_add_i32 m0, s31, 0x800
	v_add_u32_e32 v22, v20, v3
	s_cmp_eq_u32 s34, 8
	s_cbranch_scc1 .Lwp7_f2
	v_cmp_gt_u32_e32 vcc, 0x80, v3
	s_and_b64 exec, s[46:47], vcc
.Lwp7_f2:
	global_load_lds_dwordx4 v22, s[38:39] nt
	s_add_u32 s38, s38, s0
	s_addc_u32 s39, s39, 0
	s_add_i32 m0, s31, 0xc00
	v_add_u32_e32 v23, v20, v3
	global_load_lds_dwordx4 v23, s[38:39] nt
	s_add_u32 s38, s38, s0
	s_addc_u32 s39, s39, 0
	s_add_i32 m0, s31, 0x1000
	v_add_u32_e32 v22, v20, v4
	s_cmp_eq_u32 s34, 8
	s_cbranch_scc1 .Lwp7_f4
	v_cmp_gt_u32_e32 vcc, 0x80, v4
	s_and_b64 exec, s[46:47], vcc
.Lwp7_f4:
	global_load_lds_dwordx4 v22, s[38:39] nt
	s_add_u32 s38, s38, s0
	s_addc_u32 s39, s39, 0
	s_add_i32 m0, s31, 0x1400
	v_add_u32_e32 v23, v20, v4
	global_load_lds_dwordx4 v23, s[38:39] nt
	s_add_u32 s38, s38, s0
	s_addc_u32 s39, s39, 0
	s_add_i32 m0, s31, 0x1800
	v_add_u32_e32 v22, v20, v5
	s_cmp_eq_u32 s34, 8
	s_cbranch_scc1 .Lwp7_f6
	v_cmp_gt_u32_e32 vcc, 0x80, v5
	s_and_b64 exec, s[46:47], vcc
.Lwp7_f6:
	global_load_lds_dwordx4 v22, s[38:39] nt
	s_add_u32 s38, s38, s0
	s_addc_u32 s39, s39, 0
	s_add_i32 m0, s31, 0x1c00
	v_add_u32_e32 v23, v20, v5
	global_load_lds_dwordx4 v23, s[38:39] nt
	s_add_u32 s38, s38, s0
	s_addc_u32 s39, s39, 0
	s_add_i32 m0, s31, 0x2000
	v_add_u32_e32 v22, v20, v6
	s_cmp_eq_u32 s34, 8
	s_cbranch_scc1 .Lwp7_f8
	v_cmp_gt_u32_e32 vcc, 0x80, v6
	s_and_b64 exec, s[46:47], vcc
.Lwp7_f8:
	global_load_lds_dwordx4 v22, s[38:39] nt
	s_add_u32 s38, s38, s0
	s_addc_u32 s39, s39, 0
	s_add_i32 m0, s31, 0x2400
	v_add_u32_e32 v23, v20, v6
	global_load_lds_dwordx4 v23, s[38:39] nt
	s_add_u32 s38, s38, s0
	s_addc_u32 s39, s39, 0
	s_add_i32 m0, s31, 0x2800
	v_add_u32_e32 v22, v20, v7
	s_cmp_eq_u32 s34, 8
	s_cbranch_scc1 .Lwp7_f10
	v_cmp_gt_u32_e32 vcc, 0x80, v7
	s_and_b64 exec, s[46:47], vcc
.Lwp7_f10:
	global_load_lds_dwordx4 v22, s[38:39] nt
	s_add_u32 s38, s38, s0
	s_addc_u32 s39, s39, 0
	s_add_i32 m0, s31, 0x2c00
	v_add_u32_e32 v23, v20, v7
	global_load_lds_dwordx4 v23, s[38:39] nt
	s_add_u32 s38, s38, s0
	s_addc_u32 s39, s39, 0
	s_add_i32 m0, s31, 0x3000
	v_add_u32_e32 v22, v20, v8
	s_cmp_eq_u32 s34, 8
	s_cbranch_scc1 .Lwp7_f12
	v_cmp_gt_u32_e32 vcc, 0x80, v8
	s_and_b64 exec, s[46:47], vcc
.Lwp7_f12:
	global_load_lds_dwordx4 v22, s[38:39] nt
	s_add_u32 s38, s38, s0
	s_addc_u32 s39, s39, 0
	s_add_i32 m0, s31, 0x3400
	v_add_u32_e32 v23, v20, v8
	global_load_lds_dwordx4 v23, s[38:39] nt
	s_add_u32 s38, s38, s0
	s_addc_u32 s39, s39, 0
	s_add_i32 m0, s31, 0x3800
	v_add_u32_e32 v22, v20, v9
	s_cmp_eq_u32 s34, 8
	s_cbranch_scc1 .Lwp7_f14
	v_cmp_gt_u32_e32 vcc, 0x80, v9
	s_and_b64 exec, s[46:47], vcc
.Lwp7_f14:
	global_load_lds_dwordx4 v22, s[38:39] nt
	s_add_u32 s38, s38, s0
	s_addc_u32 s39, s39, 0
	s_add_i32 m0, s31, 0x3c00
	v_add_u32_e32 v23, v20, v9
	global_load_lds_dwordx4 v23, s[38:39] nt
	s_add_u32 s38, s38, s0
	s_addc_u32 s39, s39, 0
	s_mov_b64 exec, s[46:47]

; #define LAS __attribute__((address_space(3)))
; __device__ __forceinline__ unsigned cvtpk(float lo, float hi) { const f32x2 v = (f32x2){lo, hi}; const bf16v2 b = __builtin_convertvector(v, bf16v2); return __builtin_bit_cast(unsigned, b); }
; __device__ void phase_weights(const Params& p, int l, LAS unsigned char* lds) {
;     ...
;               if (u < TOT) { const WDesc d = wdesc(p, l, u); const LAS float* Tj = T + j * 4160; u32x4 w;
;                   w.x = cvtpk(Tj[(kg + 0) * 65 + r], Tj[(kg + 1) * 65 + r]); w.y = cvtpk(Tj[(kg + 2) * 65 + r], Tj[(kg + 3) * 65 + r]);
;                   w.z = cvtpk(Tj[(kg + 4) * 65 + r], Tj[(kg + 5) * 65 + r]); w.w = cvtpk(Tj[(kg + 6) * 65 + r], Tj[(kg + 7) * 65 + r]);
;                   *(u32x4*)(d.dst + (size_t)(d.r0 + r) * d.lddst + d.k0 + kg) = w; } } }
.Lwp7_s0:
	global_store_dwordx4 v21, v[40:43], s[44:45] nt
	s_add_u32 s44, s44, s1
	s_addc_u32 s45, s45, 0
	s_waitcnt lgkmcnt(0)
	s_cmp_lt_u32 s34, 3
	s_cbranch_scc1 .Lwp7_n1
	ds_read_b32 v24, v14
	ds_read_b32 v25, v14 offset:256
	ds_read_b32 v26, v14 offset:512
	ds_read_b32 v27, v14 offset:768
	ds_read_b32 v28, v14 offset:1024
	ds_read_b32 v29, v14 offset:1280
	ds_read_b32 v30, v14 offset:1536
	ds_read_b32 v31, v14 offset:1792

; #define LAS __attribute__((address_space(3)))
; __device__ __forceinline__ unsigned cvtpk(float lo, float hi) { const f32x2 v = (f32x2){lo, hi}; const bf16v2 b = __builtin_convertvector(v, bf16v2); return __builtin_bit_cast(unsigned, b); }
; __device__ void phase_weights(const Params& p, int l, LAS unsigned char* lds) {
;     ...
;               if (u < TOT) { const WDesc d = wdesc(p, l, u); const LAS float* Tj = T + j * 4160; u32x4 w;
;                   w.x = cvtpk(Tj[(kg + 0) * 65 + r], Tj[(kg + 1) * 65 + r]); w.y = cvtpk(Tj[(kg + 2) * 65 + r], Tj[(kg + 3) * 65 + r]);
;                   w.z = cvtpk(Tj[(kg + 4) * 65 + r], Tj[(kg + 5) * 65 + r]); w.w = cvtpk(Tj[(kg + 6) * 65 + r], Tj[(kg + 7) * 65 + r]);
;                   *(u32x4*)(d.dst + (size_t)(d.r0 + r) * d.lddst + d.k0 + kg) = w; } } }
.Lwp7_s1:
	global_store_dwordx4 v21, v[44:47], s[44:45] nt
	s_add_u32 s44, s44, s1
	s_addc_u32 s45, s45, 0
	s_waitcnt lgkmcnt(0)
	s_cmp_lt_u32 s34, 4
	s_cbranch_scc1 .Lwp7_n2
	ds_read_b32 v32, v15
	ds_read_b32 v33, v15 offset:256
	ds_read_b32 v34, v15 offset:512
	ds_read_b32 v35, v15 offset:768
	ds_read_b32 v36, v15 offset:1024
	ds_read_b32 v37, v15 offset:1280
	ds_read_b32 v38, v15 offset:1536
	ds_read_b32 v39, v15 offset:1792

; #define LAS __attribute__((address_space(3)))
; __device__ __forceinline__ unsigned cvtpk(float lo, float hi) { const f32x2 v = (f32x2){lo, hi}; const bf16v2 b = __builtin_convertvector(v, bf16v2); return __builtin_bit_cast(unsigned, b); }
; __device__ void phase_weights(const Params& p, int l, LAS unsigned char* lds) {
;     ...
;               if (u < TOT) { const WDesc d = wdesc(p, l, u); const LAS float* Tj = T + j * 4160; u32x4 w;
;                   w.x = cvtpk(Tj[(kg + 0) * 65 + r], Tj[(kg + 1) * 65 + r]); w.y = cvtpk(Tj[(kg + 2) * 65 + r], Tj[(kg + 3) * 65 + r]);
;                   w.z = cvtpk(Tj[(kg + 4) * 65 + r], Tj[(kg + 5) * 65 + r]); w.w = cvtpk(Tj[(kg + 6) * 65 + r], Tj[(kg + 7) * 65 + r]);
;                   *(u32x4*)(d.dst + (size_t)(d.r0 + r) * d.lddst + d.k0 + kg) = w; } } }
.Lwp7_s2:
	global_store_dwordx4 v21, v[40:43], s[44:45] nt
	s_add_u32 s44, s44, s1
	s_addc_u32 s45, s45, 0
	s_waitcnt lgkmcnt(0)
	s_cmp_lt_u32 s34, 5
	s_cbranch_scc1 .Lwp7_n3
	ds_read_b32 v24, v16
	ds_read_b32 v25, v16 offset:256
	ds_read_b32 v26, v16 offset:512
	ds_read_b32 v27, v16 offset:768
	ds_read_b32 v28, v16 offset:1024
	ds_read_b32 v29, v16 offset:1280
	ds_read_b32 v30, v16 offset:1536
	ds_read_b32 v31, v16 offset:1792

; #define LAS __attribute__((address_space(3)))
; __device__ __forceinline__ unsigned cvtpk(float lo, float hi) { const f32x2 v = (f32x2){lo, hi}; const bf16v2 b = __builtin_convertvector(v, bf16v2); return __builtin_bit_cast(unsigned, b); }
; __device__ void phase_weights(const Params& p, int l, LAS unsigned char* lds) {
;     ...
;               if (u < TOT) { const WDesc d = wdesc(p, l, u); const LAS float* Tj = T + j * 4160; u32x4 w;
;                   w.x = cvtpk(Tj[(kg + 0) * 65 + r], Tj[(kg + 1) * 65 + r]); w.y = cvtpk(Tj[(kg + 2) * 65 + r], Tj[(kg + 3) * 65 + r]);
;                   w.z = cvtpk(Tj[(kg + 4) * 65 + r], Tj[(kg + 5) * 65 + r]); w.w = cvtpk(Tj[(kg + 6) * 65 + r], Tj[(kg + 7) * 65 + r]);
;                   *(u32x4*)(d.dst + (size_t)(d.r0 + r) * d.lddst + d.k0 + kg) = w; } } }
.Lwp7_s3:
	global_store_dwordx4 v21, v[44:47], s[44:45] nt
	s_add_u32 s44, s44, s1
	s_addc_u32 s45, s45, 0
	s_waitcnt lgkmcnt(0)
	s_cmp_lt_u32 s34, 6
	s_cbranch_scc1 .Lwp7_n4
	ds_read_b32 v32, v17
	ds_read_b32 v33, v17 offset:256
	ds_read_b32 v34, v17 offset:512
	ds_read_b32 v35, v17 offset:768
	ds_read_b32 v36, v17 offset:1024
	ds_read_b32 v37, v17 offset:1280
	ds_read_b32 v38, v17 offset:1536
	ds_read_b32 v39, v17 offset:1792

; #define LAS __attribute__((address_space(3)))
; __device__ __forceinline__ unsigned cvtpk(float lo, float hi) { const f32x2 v = (f32x2){lo, hi}; const bf16v2 b = __builtin_convertvector(v, bf16v2); return __builtin_bit_cast(unsigned, b); }
; __device__ void phase_weights(const Params& p, int l, LAS unsigned char* lds) {
;     ...
;               if (u < TOT) { const WDesc d = wdesc(p, l, u); const LAS float* Tj = T + j * 4160; u32x4 w;
;                   w.x = cvtpk(Tj[(kg + 0) * 65 + r], Tj[(kg + 1) * 65 + r]); w.y = cvtpk(Tj[(kg + 2) * 65 + r], Tj[(kg + 3) * 65 + r]);
;                   w.z = cvtpk(Tj[(kg + 4) * 65 + r], Tj[(kg + 5) * 65 + r]); w.w = cvtpk(Tj[(kg + 6) * 65 + r], Tj[(kg + 7) * 65 + r]);
;                   *(u32x4*)(d.dst + (size_t)(d.r0 + r) * d.lddst + d.k0 + kg) = w; } } }
.Lwp7_s4:
	global_store_dwordx4 v21, v[40:43], s[44:45] nt
	s_add_u32 s44, s44, s1
	s_addc_u32 s45, s45, 0
	s_waitcnt lgkmcnt(0)
	s_cmp_lt_u32 s34, 7
	s_cbranch_scc1 .Lwp7_n5
	ds_read_b32 v24, v18
	ds_read_b32 v25, v18 offset:256
	ds_read_b32 v26, v18 offset:512
	ds_read_b32 v27, v18 offset:768
	ds_read_b32 v28, v18 offset:1024
	ds_read_b32 v29, v18 offset:1280
	ds_read_b32 v30, v18 offset:1536
	ds_read_b32 v31, v18 offset:1792

; #define LAS __attribute__((address_space(3)))
; __device__ __forceinline__ unsigned cvtpk(float lo, float hi) { const f32x2 v = (f32x2){lo, hi}; const bf16v2 b = __builtin_convertvector(v, bf16v2); return __builtin_bit_cast(unsigned, b); }
; __device__ void phase_weights(const Params& p, int l, LAS unsigned char* lds) {
;     ...
;               if (u < TOT) { const WDesc d = wdesc(p, l, u); const LAS float* Tj = T + j * 4160; u32x4 w;
;                   w.x = cvtpk(Tj[(kg + 0) * 65 + r], Tj[(kg + 1) * 65 + r]); w.y = cvtpk(Tj[(kg + 2) * 65 + r], Tj[(kg + 3) * 65 + r]);
;                   w.z = cvtpk(Tj[(kg + 4) * 65 + r], Tj[(kg + 5) * 65 + r]); w.w = cvtpk(Tj[(kg + 6) * 65 + r], Tj[(kg + 7) * 65 + r]);
;                   *(u32x4*)(d.dst + (size_t)(d.r0 + r) * d.lddst + d.k0 + kg) = w; } } }
.Lwp7_s5:
	global_store_dwordx4 v21, v[44:47], s[44:45] nt
	s_add_u32 s44, s44, s1
	s_addc_u32 s45, s45, 0
	s_waitcnt lgkmcnt(0)
	s_cmp_lt_u32 s34, 8
	s_cbranch_scc1 .Lwp7_n6
	ds_read_b32 v32, v19
	ds_read_b32 v33, v19 offset:256
	ds_read_b32 v34, v19 offset:512
	ds_read_b32 v35, v19 offset:768
	ds_read_b32 v36, v19 offset:1024
	ds_read_b32 v37, v19 offset:1280
	ds_read_b32 v38, v19 offset:1536
	ds_read_b32 v39, v19 offset:1792

; #define LAS __attribute__((address_space(3)))
; __device__ __forceinline__ unsigned cvtpk(float lo, float hi) { const f32x2 v = (f32x2){lo, hi}; const bf16v2 b = __builtin_convertvector(v, bf16v2); return __builtin_bit_cast(unsigned, b); }
; __device__ void phase_weights(const Params& p, int l, LAS unsigned char* lds) {
;     ...
;               if (u < TOT) { const WDesc d = wdesc(p, l, u); const LAS float* Tj = T + j * 4160; u32x4 w;
;                   w.x = cvtpk(Tj[(kg + 0) * 65 + r], Tj[(kg + 1) * 65 + r]); w.y = cvtpk(Tj[(kg + 2) * 65 + r], Tj[(kg + 3) * 65 + r]);
;                   w.z = cvtpk(Tj[(kg + 4) * 65 + r], Tj[(kg + 5) * 65 + r]); w.w = cvtpk(Tj[(kg + 6) * 65 + r], Tj[(kg + 7) * 65 + r]);
;                   *(u32x4*)(d.dst + (size_t)(d.r0 + r) * d.lddst + d.k0 + kg) = w; } } }
.Lwp7_s6:
	global_store_dwordx4 v21, v[40:43], s[44:45] nt
	s_add_u32 s44, s44, s1
	s_addc_u32 s45, s45, 0
	s_waitcnt lgkmcnt(0)
	s_cmp_lt_u32 s34, 8
	s_cbranch_scc1 .Lwp7_z7
	v_cvt_pk_bf16_f32 v44, v32, v33
	v_cvt_pk_bf16_f32 v45, v34, v35
	v_cvt_pk_bf16_f32 v46, v36, v37
	v_cvt_pk_bf16_f32 v47, v38, v39
	s_branch .Lwp7_s7

; #define LAS __attribute__((address_space(3)))
; __device__ __forceinline__ unsigned cvtpk(float lo, float hi) { const f32x2 v = (f32x2){lo, hi}; const bf16v2 b = __builtin_convertvector(v, bf16v2); return __builtin_bit_cast(unsigned, b); }
; __device__ void phase_weights(const Params& p, int l, LAS unsigned char* lds) {
;     ...
;               if (u < TOT) { const WDesc d = wdesc(p, l, u); const LAS float* Tj = T + j * 4160; u32x4 w;
;                   w.x = cvtpk(Tj[(kg + 0) * 65 + r], Tj[(kg + 1) * 65 + r]); w.y = cvtpk(Tj[(kg + 2) * 65 + r], Tj[(kg + 3) * 65 + r]);
;                   w.z = cvtpk(Tj[(kg + 4) * 65 + r], Tj[(kg + 5) * 65 + r]); w.w = cvtpk(Tj[(kg + 6) * 65 + r], Tj[(kg + 7) * 65 + r]);
;                   *(u32x4*)(d.dst + (size_t)(d.r0 + r) * d.lddst + d.k0 + kg) = w; } } }
.Lwp7_s7:
	global_store_dwordx4 v21, v[44:47], s[44:45] nt
	s_add_u32 s27, s27, 0x400
	s_branch .Lwp7_round

; #define LAS __attribute__((address_space(3)))
; __device__ __forceinline__ unsigned cvtpk(float lo, float hi) { const f32x2 v = (f32x2){lo, hi}; const bf16v2 b = __builtin_convertvector(v, bf16v2); return __builtin_bit_cast(unsigned, b); }
; __device__ void phase_weights(const Params& p, int l, LAS unsigned char* lds) {
;     ...
;               if (u < TOT) { const WDesc d = wdesc(p, l, u); const LAS float* Tj = T + j * 4160; u32x4 w;
;                   w.x = cvtpk(Tj[(kg + 0) * 65 + r], Tj[(kg + 1) * 65 + r]); w.y = cvtpk(Tj[(kg + 2) * 65 + r], Tj[(kg + 3) * 65 + r]);
;                   w.z = cvtpk(Tj[(kg + 4) * 65 + r], Tj[(kg + 5) * 65 + r]); w.w = cvtpk(Tj[(kg + 6) * 65 + r], Tj[(kg + 7) * 65 + r]);
;                   *(u32x4*)(d.dst + (size_t)(d.r0 + r) * d.lddst + d.k0 + kg) = w; } } }
.Lwp1_s7:
	global_store_dwordx4 v21, v[44:47], s[44:45] nt
	s_add_u32 s27, s27, 0x200
	s_branch .Lwp1_round

; #define LAS __attribute__((address_space(3)))
; __device__ __forceinline__ unsigned cvtpk(float lo, float hi) { const f32x2 v = (f32x2){lo, hi}; const bf16v2 b = __builtin_convertvector(v, bf16v2); return __builtin_bit_cast(unsigned, b); }
; __device__ void phase_weights(const Params& p, int l, LAS unsigned char* lds) {
;     ...
;               if (u < TOT) { const WDesc d = wdesc(p, l, u); const LAS float* Tj = T + j * 4160; u32x4 w;
;                   w.x = cvtpk(Tj[(kg + 0) * 65 + r], Tj[(kg + 1) * 65 + r]); w.y = cvtpk(Tj[(kg + 2) * 65 + r], Tj[(kg + 3) * 65 + r]);
;                   w.z = cvtpk(Tj[(kg + 4) * 65 + r], Tj[(kg + 5) * 65 + r]); w.w = cvtpk(Tj[(kg + 6) * 65 + r], Tj[(kg + 7) * 65 + r]);
;                   *(u32x4*)(d.dst + (size_t)(d.r0 + r) * d.lddst + d.k0 + kg) = w; } } }
.Lwp0_s7:
	global_store_dwordx4 v21, v[44:47], s[44:45] nt
	s_add_u32 s27, s27, 0x800
	s_branch .Lwp0_round
